# mixer phases: one static s_setprio 1 for waves 4-7 at phase entry, back to 0 at phase end
# baseline (speedup 1.0000x reference)
; template <class T> DI T* optr(T* p) { unsigned long long v = (unsigned long long)p; asm volatile("" : "+s"(v)); return (T*)(GAS T*)v; }
; DI void mixer_phase(char* shm, const Params& P, int l, int hf, int ph) {
;   __shared__ int s_item;
;   unsigned* ctr = (unsigned*)(optr(P.ws) + WS_CTR) + ph;
;   const int nitems = 128 + 64 + 512 + (hf ? 512 : 0);
;   for (;;) {
;     __syncthreads();
;     if (threadIdx.x == 0) s_item = (int)atomicAdd(ctr, 1u);
;     __syncthreads();
;     int it = s_item;
;     if (it >= nitems) break;
.LBB0_59:
	v_readfirstlane_b32 s4, v242
	s_cmp_lt_u32 s4, 0x100
	s_cbranch_scc1 .Lmix_prio_skip
	s_setprio 1

; DI void mixer_phase(char* shm, const Params& P, int l, int hf, int ph) {
;     ...
;   for (;;) {
;     __syncthreads();
;     if (threadIdx.x == 0) s_item = (int)atomicAdd(ctr, 1u);
;     __syncthreads();
;     int it = s_item;
;     if (it >= nitems) break;
;     const int nsamp = hf ? 512 : 0;
;     if (it < 128) { ssd_prompt_item(shm, P, l, hf, hf * 8 + (it >> 4), it & 15); }
;     else if ((it -= 128) < 64) { ret_prompt_item(shm, P, l, hf, hf * 8 + (it >> 3), it & 7); }
;     else if ((it -= 64) < nsamp) {
;       if (it < 256) { ssd_sample_item(shm, P, l, it >> 1, it & 1); }
;       else if ((it -= 256) < 128) { ret_sample_item(shm, P, l, it); }
;       else { it -= 128; att_sample_item(shm, P, l, it); }
;     }
;     else { it -= nsamp; att_prompt_item(shm, P, l, hf, hf * 8 + (it >> 6), (it >> 2) & 15, it & 3); }
;   }
; }
.LBB0_278:
	s_setprio 0
	v_readlane_b32 s78, v255, 7
	v_readlane_b32 s66, v254, 51
	s_mov_b64 s[0:1], 0
	v_readlane_b32 s79, v255, 8
	v_readlane_b32 s82, v255, 9
	v_readlane_b32 s67, v254, 52
